# on top of v60: the four shift@W (swp_matrix) loops that run after the mixer RES GEMM prefetch the next weight row while reducing the current one
# speedup vs baseline: 1.0012x; 1.0004x over previous
.LBB0_396:
	s_cmp_eq_u32 s72, 3
	s_cselect_b64 s[0:1], -1, 0
	s_xor_b64 s[2:3], s[12:13], -1
	s_or_b64 s[0:1], s[2:3], s[0:1]
	s_and_b64 vcc, exec, s[0:1]
	s_cbranch_vccnz .LBB0_446
	s_add_i32 s3, s72, 1
	s_bitcmp1_b32 s3, 0
	s_mul_i32 s0, s3, 0xc000
	v_readlane_b32 s4, v255, 41
	s_cselect_b32 s2, 0x11000, 0
	v_readlane_b32 s5, v255, 42
	s_add_u32 s6, s4, s0
	s_addc_u32 s7, s5, 0
	s_cmpk_lt_i32 s90, 0x1600
	s_cselect_b64 s[8:9], -1, 0
	s_cmpk_gt_i32 s90, 0x15ff
	v_lshlrev_b32_e32 v1, 3, v200
	s_cbranch_scc1 .LBB0_408
	v_lshlrev_b32_e32 v190, 2, v1
	v_lshl_add_u64 v[58:59], s[6:7], 0, v[190:191]
	s_mov_b64 s[0:1], 0x1000
	s_waitcnt vmcnt(3)
	v_lshl_add_u64 v[22:23], v[58:59], 0, s[0:1]
	s_mov_b64 s[0:1], 0x1800
	v_add_co_u32_e32 v26, vcc, 0x1000, v58
	v_lshl_add_u64 v[30:31], v[58:59], 0, s[0:1]
	s_mov_b64 s[0:1], 0x2000
	v_addc_co_u32_e32 v27, vcc, 0, v59, vcc
	v_lshl_add_u64 v[38:39], v[58:59], 0, s[0:1]
	s_mov_b64 s[0:1], 0x2800
	v_add_co_u32_e32 v42, vcc, 0x2000, v58
	v_lshl_add_u64 v[46:47], v[58:59], 0, s[0:1]
	s_mov_b64 s[0:1], 0x3000
	v_addc_co_u32_e32 v43, vcc, 0, v59, vcc
	v_lshl_add_u64 v[54:55], v[58:59], 0, s[0:1]
	s_movk_i32 s0, 0x3000
	global_load_dwordx4 v[2:5], v190, s[6:7] offset:16
	s_waitcnt lgkmcnt(1)
	global_load_dwordx4 v[6:9], v190, s[6:7]
	s_waitcnt lgkmcnt(0)
	global_load_dwordx4 v[10:13], v190, s[6:7] offset:2064
	global_load_dwordx4 v[14:17], v190, s[6:7] offset:2048
	v_add_co_u32_e32 v60, vcc, s0, v58
	s_mov_b64 s[0:1], 0x3800
	s_nop 0
	v_addc_co_u32_e32 v61, vcc, 0, v59, vcc
	v_lshl_add_u64 v[62:63], v[58:59], 0, s[0:1]
	global_load_dwordx4 v[18:21], v[26:27], off
	s_nop 0
	global_load_dwordx4 v[22:25], v[22:23], off offset:16
	s_nop 0
	global_load_dwordx4 v[26:29], v[26:27], off offset:2048
	s_nop 0
	global_load_dwordx4 v[30:33], v[30:31], off offset:16
	s_nop 0
	global_load_dwordx4 v[34:37], v[42:43], off
	s_nop 0
	global_load_dwordx4 v[38:41], v[38:39], off offset:16
	s_nop 0
	global_load_dwordx4 v[42:45], v[42:43], off offset:2048
	s_nop 0
	global_load_dwordx4 v[46:49], v[46:47], off offset:16
	s_nop 0
	global_load_dwordx4 v[50:53], v[60:61], off
	s_nop 0
	global_load_dwordx4 v[54:57], v[54:55], off offset:16
	s_nop 0
	global_load_dwordx4 v[58:61], v[60:61], off offset:2048
	s_nop 0
	global_load_dwordx4 v[62:65], v[62:63], off offset:16
	v_and_b32_e32 v66, 64, v227
	v_add_u32_e32 v66, 64, v66
	v_xor_b32_e32 v67, 1, v227
	v_cmp_lt_i32_e32 vcc, v67, v66
	s_ashr_i32 s91, s90, 31
	s_lshl_b32 s10, s2, 2
	v_cndmask_b32_e32 v67, v227, v67, vcc
	v_lshlrev_b32_e32 v86, 2, v67
	v_xor_b32_e32 v67, 2, v227
	v_cmp_lt_i32_e32 vcc, v67, v66
	s_lshl_b64 s[0:1], s[90:91], 2
	s_add_u32 s0, s10, s0
	v_cndmask_b32_e32 v67, v227, v67, vcc
	v_lshlrev_b32_e32 v87, 2, v67
	v_xor_b32_e32 v67, 4, v227
	v_cmp_lt_i32_e32 vcc, v67, v66
	s_addc_u32 s1, 0, s1
	v_readlane_b32 s10, v255, 52
	v_cndmask_b32_e32 v67, v227, v67, vcc
	v_lshlrev_b32_e32 v88, 2, v67
	v_xor_b32_e32 v67, 8, v227
	v_cmp_lt_i32_e32 vcc, v67, v66
	s_add_u32 s0, s10, s0
	v_readlane_b32 s10, v255, 53
	v_cndmask_b32_e32 v67, v227, v67, vcc
	v_lshlrev_b32_e32 v89, 2, v67
	v_xor_b32_e32 v67, 16, v227
	v_cmp_lt_i32_e32 vcc, v67, v66
	s_addc_u32 s1, s10, s1
	s_ashr_i32 s93, s92, 31
	v_cndmask_b32_e32 v67, v227, v67, vcc
	v_lshlrev_b32_e32 v90, 2, v67
	v_xor_b32_e32 v67, 32, v227
	v_cmp_lt_i32_e32 vcc, v67, v66
	s_lshl_b64 s[10:11], s[92:93], 2
	v_readlane_b32 s12, v255, 54
	v_cndmask_b32_e32 v66, v227, v67, vcc
	v_lshlrev_b32_e32 v91, 2, v66
	v_mul_u32_u24_e32 v66, 0x1600, v200
	v_lshlrev_b32_e32 v190, 2, v66
	v_lshl_add_u64 v[66:67], s[0:1], 0, v[190:191]
	s_lshl_b64 s[0:1], s[90:91], 11
	v_readlane_b32 s13, v255, 55
	s_add_u32 s0, s12, s0
	v_lshlrev_b32_e32 v190, 4, v200
	s_addc_u32 s1, s13, s1
	v_lshl_add_u64 v[68:69], s[0:1], 0, v[190:191]
	s_mov_b64 s[0:1], 0xb00000
	v_cmp_gt_u32_e32 vcc, 4, v200
	v_cmp_eq_u32_e64 s[4:5], 2, v200
	v_readlane_b32 s91, v255, 34
	v_lshl_add_u64 v[68:69], v[68:69], 0, s[0:1]
	s_lshl_b64 s[12:13], s[92:93], 11
	v_readlane_b32 s93, v255, 35
	s_mov_b32 s18, s90
	global_load_dwordx4 v[104:107], v[68:69], off
	global_load_dwordx4 v[108:111], v[68:69], off offset:1024
	s_branch .LBB0_402

.LBB0_402:
	s_waitcnt lgkmcnt(0)
	s_waitcnt vmcnt(0)
	v_mov_b32_e32 v70, v104
	v_mov_b32_e32 v71, v105
	v_mov_b32_e32 v72, v106
	v_mov_b32_e32 v73, v107
	v_mov_b32_e32 v92, v108
	v_mov_b32_e32 v93, v109
	v_mov_b32_e32 v94, v110
	v_mov_b32_e32 v95, v111
	v_lshl_add_u64 v[112:113], v[68:69], 0, s[12:13]
	global_load_dwordx4 v[104:107], v[112:113], off
	global_load_dwordx4 v[108:111], v[112:113], off offset:1024
	v_lshlrev_b32_e32 v84, 16, v72
	v_and_b32_e32 v85, 0xffff0000, v72
	v_lshlrev_b32_e32 v82, 16, v73
	v_and_b32_e32 v83, 0xffff0000, v73
	v_lshlrev_b32_e32 v78, 16, v70
	v_and_b32_e32 v79, 0xffff0000, v70
	v_lshlrev_b32_e32 v80, 16, v71
	v_and_b32_e32 v81, 0xffff0000, v71
	v_lshlrev_b32_e32 v76, 16, v92
	v_and_b32_e32 v77, 0xffff0000, v92
	v_lshlrev_b32_e32 v74, 16, v93
	v_and_b32_e32 v75, 0xffff0000, v93
	v_lshlrev_b32_e32 v70, 16, v94
	v_and_b32_e32 v71, 0xffff0000, v94
	v_lshlrev_b32_e32 v72, 16, v95
	v_and_b32_e32 v73, 0xffff0000, v95
	v_pk_mul_f32 v[92:93], v[2:3], v[84:85]
	v_pk_mul_f32 v[94:95], v[4:5], v[82:83]
	v_pk_fma_f32 v[92:93], v[6:7], v[78:79], v[92:93]
	v_pk_fma_f32 v[94:95], v[8:9], v[80:81], v[94:95]
	v_pk_fma_f32 v[92:93], v[14:15], v[76:77], v[92:93]
	v_pk_fma_f32 v[94:95], v[16:17], v[74:75], v[94:95]
	v_pk_fma_f32 v[92:93], v[10:11], v[70:71], v[92:93]
	v_pk_fma_f32 v[94:95], v[12:13], v[72:73], v[94:95]
	v_add_f32_e32 v92, v92, v93
	v_add_f32_e32 v93, v94, v95
	v_pk_mul_f32 v[94:95], v[22:23], v[84:85]
	v_pk_mul_f32 v[96:97], v[24:25], v[82:83]
	v_pk_fma_f32 v[94:95], v[18:19], v[78:79], v[94:95]
	v_pk_fma_f32 v[96:97], v[20:21], v[80:81], v[96:97]
	v_pk_fma_f32 v[94:95], v[26:27], v[76:77], v[94:95]
	v_pk_fma_f32 v[96:97], v[28:29], v[74:75], v[96:97]
	v_pk_fma_f32 v[94:95], v[30:31], v[70:71], v[94:95]
	v_pk_fma_f32 v[96:97], v[32:33], v[72:73], v[96:97]
	v_add_f32_e32 v94, v94, v95
	v_add_f32_e32 v95, v96, v97
	v_pk_mul_f32 v[96:97], v[38:39], v[84:85]
	v_pk_mul_f32 v[98:99], v[40:41], v[82:83]
	v_pk_mul_f32 v[84:85], v[54:55], v[84:85]
	v_pk_mul_f32 v[82:83], v[56:57], v[82:83]
	v_pk_fma_f32 v[98:99], v[36:37], v[80:81], v[98:99]
	v_pk_fma_f32 v[96:97], v[34:35], v[78:79], v[96:97]
	v_pk_fma_f32 v[80:81], v[52:53], v[80:81], v[82:83]
	v_pk_fma_f32 v[78:79], v[50:51], v[78:79], v[84:85]
	v_pk_fma_f32 v[96:97], v[42:43], v[76:77], v[96:97]
	v_pk_fma_f32 v[98:99], v[44:45], v[74:75], v[98:99]
	v_pk_fma_f32 v[76:77], v[58:59], v[76:77], v[78:79]
	v_pk_fma_f32 v[74:75], v[60:61], v[74:75], v[80:81]
	v_pk_fma_f32 v[98:99], v[48:49], v[72:73], v[98:99]
	v_pk_fma_f32 v[96:97], v[46:47], v[70:71], v[96:97]
	v_pk_fma_f32 v[72:73], v[64:65], v[72:73], v[74:75]
	v_pk_fma_f32 v[70:71], v[62:63], v[70:71], v[76:77]
	v_add_f32_e32 v96, v96, v97
	v_add_f32_e32 v97, v98, v99
	v_add_f32_e32 v70, v70, v71
	v_add_f32_e32 v71, v72, v73
	v_add_f32_e32 v92, v92, v93
	v_add_f32_e32 v94, v94, v95
	v_add_f32_e32 v96, v96, v97
	v_add_f32_e32 v70, v70, v71
	ds_bpermute_b32 v93, v86, v92
	ds_bpermute_b32 v95, v86, v94
	ds_bpermute_b32 v97, v86, v96
	ds_bpermute_b32 v71, v86, v70
	s_waitcnt lgkmcnt(3)
	v_add_f32_e32 v92, v92, v93
	s_waitcnt lgkmcnt(2)
	v_add_f32_e32 v94, v94, v95
	s_waitcnt lgkmcnt(1)
	v_add_f32_e32 v96, v96, v97
	s_waitcnt lgkmcnt(0)
	v_add_f32_e32 v70, v70, v71
	ds_bpermute_b32 v93, v87, v92
	ds_bpermute_b32 v95, v87, v94
	ds_bpermute_b32 v97, v87, v96
	ds_bpermute_b32 v71, v87, v70
	s_waitcnt lgkmcnt(3)
	v_add_f32_e32 v92, v92, v93
	s_waitcnt lgkmcnt(2)
	v_add_f32_e32 v94, v94, v95
	s_waitcnt lgkmcnt(1)
	v_add_f32_e32 v96, v96, v97
	s_waitcnt lgkmcnt(0)
	v_add_f32_e32 v70, v70, v71
	ds_bpermute_b32 v93, v88, v92
	ds_bpermute_b32 v95, v88, v94
	ds_bpermute_b32 v97, v88, v96
	ds_bpermute_b32 v71, v88, v70
	s_waitcnt lgkmcnt(3)
	v_add_f32_e32 v92, v92, v93
	s_waitcnt lgkmcnt(2)
	v_add_f32_e32 v94, v94, v95
	s_waitcnt lgkmcnt(1)
	v_add_f32_e32 v96, v96, v97
	s_waitcnt lgkmcnt(0)
	v_add_f32_e32 v70, v70, v71
	ds_bpermute_b32 v93, v89, v92
	ds_bpermute_b32 v95, v89, v94
	ds_bpermute_b32 v97, v89, v96
	ds_bpermute_b32 v71, v89, v70
	s_waitcnt lgkmcnt(3)
	v_add_f32_e32 v92, v92, v93
	s_waitcnt lgkmcnt(2)
	v_add_f32_e32 v94, v94, v95
	s_waitcnt lgkmcnt(1)
	v_add_f32_e32 v96, v96, v97
	s_waitcnt lgkmcnt(0)
	v_add_f32_e32 v70, v70, v71
	ds_bpermute_b32 v93, v90, v92
	ds_bpermute_b32 v95, v90, v94
	ds_bpermute_b32 v97, v90, v96
	ds_bpermute_b32 v71, v90, v70
	s_waitcnt lgkmcnt(3)
	v_add_f32_e32 v92, v92, v93
	s_waitcnt lgkmcnt(2)
	v_add_f32_e32 v94, v94, v95
	s_waitcnt lgkmcnt(1)
	v_add_f32_e32 v96, v96, v97
	s_waitcnt lgkmcnt(0)
	v_add_f32_e32 v70, v70, v71
	ds_bpermute_b32 v93, v91, v92
	ds_bpermute_b32 v95, v91, v94
	ds_bpermute_b32 v97, v91, v96
	ds_bpermute_b32 v72, v91, v70
	s_and_saveexec_b64 s[14:15], vcc
	s_cbranch_execz .LBB0_401
	s_waitcnt lgkmcnt(3)
	v_add_f32_e32 v71, v92, v93
	v_cmp_lt_i32_e64 s[0:1], 0, v200
	s_and_saveexec_b64 s[16:17], s[0:1]
	s_cbranch_execz .LBB0_400
	v_cmp_ne_u32_e64 s[0:1], 1, v200
	s_and_saveexec_b64 s[26:27], s[0:1]
	s_xor_b64 s[0:1], exec, s[26:27]
	s_cbranch_execz .LBB0_406
	s_waitcnt lgkmcnt(1)
	v_add_f32_e32 v71, v96, v97
	s_waitcnt lgkmcnt(0)
	v_add_f32_e32 v70, v70, v72
	v_cndmask_b32_e64 v71, v70, v71, s[4:5]

.LBB0_408:
	s_cmp_eq_u32 s72, 0
	s_movk_i32 s0, 0x600
	s_cselect_b32 s18, 0xc00, s0
	s_cmp_ge_i32 s90, s18
	s_cbranch_scc1 .LBB0_419
	v_lshlrev_b32_e32 v190, 2, v1
	v_lshl_add_u64 v[50:51], s[6:7], 0, v[190:191]
	s_mov_b64 s[0:1], 0x4000
	v_lshl_add_u64 v[14:15], v[50:51], 0, s[0:1]
	v_add_co_u32_e32 v2, vcc, 0x4000, v50
	s_mov_b64 s[0:1], 0x5000
	s_nop 0
	v_addc_co_u32_e32 v3, vcc, 0, v51, vcc
	s_waitcnt vmcnt(3)
	v_lshl_add_u64 v[22:23], v[50:51], 0, s[0:1]
	s_mov_b64 s[0:1], 0x5800
	v_add_co_u32_e32 v26, vcc, 0x5000, v50
	v_lshl_add_u64 v[30:31], v[50:51], 0, s[0:1]
	s_mov_b64 s[0:1], 0x6000
	v_addc_co_u32_e32 v27, vcc, 0, v51, vcc
	v_lshl_add_u64 v[34:35], v[50:51], 0, s[0:1]
	s_movk_i32 s0, 0x6000
	v_add_co_u32_e32 v38, vcc, s0, v50
	s_movk_i32 s0, 0x7000
	s_nop 0
	v_addc_co_u32_e32 v39, vcc, 0, v51, vcc
	v_add_co_u32_e32 v58, vcc, s0, v50
	s_mov_b64 s[0:1], 0x6800
	v_lshl_add_u64 v[42:43], v[50:51], 0, s[0:1]
	s_mov_b64 s[0:1], 0x7000
	v_lshl_add_u64 v[46:47], v[50:51], 0, s[0:1]
	s_mov_b64 s[0:1], 0x7800
	v_addc_co_u32_e32 v59, vcc, 0, v51, vcc
	v_lshl_add_u64 v[62:63], v[50:51], 0, s[0:1]
	global_load_dwordx4 v[2:5], v[2:3], off
	s_waitcnt lgkmcnt(1)
	global_load_dwordx4 v[6:9], v[14:15], off offset:2064
	s_waitcnt lgkmcnt(0)
	global_load_dwordx4 v[10:13], v[14:15], off offset:16
	s_nop 0
	global_load_dwordx4 v[14:17], v[14:15], off offset:2048
	s_nop 0
	global_load_dwordx4 v[18:21], v[26:27], off
	s_nop 0
	global_load_dwordx4 v[22:25], v[22:23], off offset:16
	s_nop 0
	global_load_dwordx4 v[26:29], v[26:27], off offset:2048
	s_nop 0
	global_load_dwordx4 v[30:33], v[30:31], off offset:16
	s_nop 0
	global_load_dwordx4 v[34:37], v[34:35], off offset:16
	s_nop 0
	global_load_dwordx4 v[38:41], v[38:39], off offset:2048
	s_nop 0
	global_load_dwordx4 v[42:45], v[42:43], off offset:16
	s_nop 0
	global_load_dwordx4 v[46:49], v[46:47], off offset:16
	s_nop 0
	global_load_dwordx4 v[50:53], v[58:59], off
	global_load_dwordx4 v[54:57], v[58:59], off offset:2048
	s_nop 0
	global_load_dwordx4 v[58:61], v[58:59], off offset:-4096
	s_nop 0
	global_load_dwordx4 v[62:65], v[62:63], off offset:16
	v_and_b32_e32 v66, 64, v227
	v_add_u32_e32 v66, 64, v66
	v_xor_b32_e32 v67, 1, v227
	v_cmp_lt_i32_e32 vcc, v67, v66
	s_ashr_i32 s91, s90, 31
	s_lshl_b32 s10, s2, 2
	v_cndmask_b32_e32 v67, v227, v67, vcc
	v_lshlrev_b32_e32 v86, 2, v67
	v_xor_b32_e32 v67, 2, v227
	v_cmp_lt_i32_e32 vcc, v67, v66
	s_lshl_b64 s[0:1], s[90:91], 2
	s_add_u32 s0, s10, s0
	v_cndmask_b32_e32 v67, v227, v67, vcc
	v_lshlrev_b32_e32 v87, 2, v67
	v_xor_b32_e32 v67, 4, v227
	v_cmp_lt_i32_e32 vcc, v67, v66
	s_addc_u32 s1, 0, s1
	s_add_u32 s0, s34, s0
	v_cndmask_b32_e32 v67, v227, v67, vcc
	v_lshlrev_b32_e32 v88, 2, v67
	v_xor_b32_e32 v67, 8, v227
	v_cmp_lt_i32_e32 vcc, v67, v66
	s_addc_u32 s1, s35, s1
	s_ashr_i32 s93, s92, 31
	v_cndmask_b32_e32 v67, v227, v67, vcc
	v_lshlrev_b32_e32 v89, 2, v67
	v_xor_b32_e32 v67, 16, v227
	v_cmp_lt_i32_e32 vcc, v67, v66
	s_lshl_b64 s[10:11], s[92:93], 2
	v_readlane_b32 s12, v255, 54
	v_cndmask_b32_e32 v67, v227, v67, vcc
	v_lshlrev_b32_e32 v90, 2, v67
	v_xor_b32_e32 v67, 32, v227
	v_cmp_lt_i32_e32 vcc, v67, v66
	v_readlane_b32 s13, v255, 55
	v_cmp_eq_u32_e64 s[4:5], 2, v200
	v_cndmask_b32_e32 v66, v227, v67, vcc
	v_lshlrev_b32_e32 v91, 2, v66
	v_mul_u32_u24_e32 v66, s18, v200
	v_lshlrev_b32_e32 v190, 2, v66
	v_lshl_add_u64 v[66:67], s[0:1], 0, v[190:191]
	s_mov_b64 s[0:1], 0xa16000
	v_lshl_add_u64 v[66:67], v[66:67], 0, s[0:1]
	s_lshl_b64 s[0:1], s[90:91], 11
	s_add_u32 s0, s12, s0
	v_lshlrev_b32_e32 v190, 4, v200
	s_addc_u32 s1, s13, s1
	v_lshl_add_u64 v[68:69], s[0:1], 0, v[190:191]
	s_mov_b64 s[0:1], 0x2d00000
	v_cmp_gt_u32_e32 vcc, 4, v200
	v_lshl_add_u64 v[68:69], v[68:69], 0, s[0:1]
	s_lshl_b64 s[12:13], s[92:93], 11
	s_mov_b32 s19, s90
	global_load_dwordx4 v[104:107], v[68:69], off
	global_load_dwordx4 v[108:111], v[68:69], off offset:1024
	s_branch .LBB0_413

.LBB0_413:
	s_waitcnt lgkmcnt(0)
	s_waitcnt vmcnt(0)
	v_mov_b32_e32 v70, v104
	v_mov_b32_e32 v71, v105
	v_mov_b32_e32 v72, v106
	v_mov_b32_e32 v73, v107
	v_mov_b32_e32 v92, v108
	v_mov_b32_e32 v93, v109
	v_mov_b32_e32 v94, v110
	v_mov_b32_e32 v95, v111
	v_lshl_add_u64 v[112:113], v[68:69], 0, s[12:13]
	global_load_dwordx4 v[104:107], v[112:113], off
	global_load_dwordx4 v[108:111], v[112:113], off offset:1024
	v_lshlrev_b32_e32 v84, 16, v72
	v_and_b32_e32 v85, 0xffff0000, v72
	v_lshlrev_b32_e32 v82, 16, v73
	v_and_b32_e32 v83, 0xffff0000, v73
	v_lshlrev_b32_e32 v78, 16, v70
	v_and_b32_e32 v79, 0xffff0000, v70
	v_lshlrev_b32_e32 v80, 16, v71
	v_and_b32_e32 v81, 0xffff0000, v71
	v_lshlrev_b32_e32 v76, 16, v92
	v_and_b32_e32 v77, 0xffff0000, v92
	v_lshlrev_b32_e32 v74, 16, v93
	v_and_b32_e32 v75, 0xffff0000, v93
	v_lshlrev_b32_e32 v70, 16, v94
	v_and_b32_e32 v71, 0xffff0000, v94
	v_lshlrev_b32_e32 v72, 16, v95
	v_and_b32_e32 v73, 0xffff0000, v95
	v_pk_mul_f32 v[92:93], v[10:11], v[84:85]
	v_pk_mul_f32 v[94:95], v[12:13], v[82:83]
	v_pk_fma_f32 v[92:93], v[2:3], v[78:79], v[92:93]
	v_pk_fma_f32 v[94:95], v[4:5], v[80:81], v[94:95]
	v_pk_fma_f32 v[92:93], v[14:15], v[76:77], v[92:93]
	v_pk_fma_f32 v[94:95], v[16:17], v[74:75], v[94:95]
	v_pk_fma_f32 v[92:93], v[6:7], v[70:71], v[92:93]
	v_pk_fma_f32 v[94:95], v[8:9], v[72:73], v[94:95]
	v_add_f32_e32 v92, v92, v93
	v_add_f32_e32 v93, v94, v95
	v_pk_mul_f32 v[94:95], v[22:23], v[84:85]
	v_pk_mul_f32 v[96:97], v[24:25], v[82:83]
	v_pk_fma_f32 v[94:95], v[18:19], v[78:79], v[94:95]
	v_pk_fma_f32 v[96:97], v[20:21], v[80:81], v[96:97]
	v_pk_fma_f32 v[94:95], v[26:27], v[76:77], v[94:95]
	v_pk_fma_f32 v[96:97], v[28:29], v[74:75], v[96:97]
	v_pk_fma_f32 v[94:95], v[30:31], v[70:71], v[94:95]
	v_pk_fma_f32 v[96:97], v[32:33], v[72:73], v[96:97]
	v_add_f32_e32 v94, v94, v95
	v_add_f32_e32 v95, v96, v97
	v_pk_mul_f32 v[96:97], v[34:35], v[84:85]
	v_pk_mul_f32 v[98:99], v[36:37], v[82:83]
	v_pk_mul_f32 v[84:85], v[46:47], v[84:85]
	v_pk_mul_f32 v[82:83], v[48:49], v[82:83]
	v_pk_fma_f32 v[98:99], v[60:61], v[80:81], v[98:99]
	v_pk_fma_f32 v[96:97], v[58:59], v[78:79], v[96:97]
	v_pk_fma_f32 v[80:81], v[52:53], v[80:81], v[82:83]
	v_pk_fma_f32 v[78:79], v[50:51], v[78:79], v[84:85]
	v_pk_fma_f32 v[96:97], v[38:39], v[76:77], v[96:97]
	v_pk_fma_f32 v[98:99], v[40:41], v[74:75], v[98:99]
	v_pk_fma_f32 v[76:77], v[54:55], v[76:77], v[78:79]
	v_pk_fma_f32 v[74:75], v[56:57], v[74:75], v[80:81]
	v_pk_fma_f32 v[98:99], v[44:45], v[72:73], v[98:99]
	v_pk_fma_f32 v[96:97], v[42:43], v[70:71], v[96:97]
	v_pk_fma_f32 v[72:73], v[64:65], v[72:73], v[74:75]
	v_pk_fma_f32 v[70:71], v[62:63], v[70:71], v[76:77]
	v_add_f32_e32 v96, v96, v97
	v_add_f32_e32 v97, v98, v99
	v_add_f32_e32 v70, v70, v71
	v_add_f32_e32 v71, v72, v73
	v_add_f32_e32 v92, v92, v93
	v_add_f32_e32 v94, v94, v95
	v_add_f32_e32 v96, v96, v97
	v_add_f32_e32 v70, v70, v71
	ds_bpermute_b32 v93, v86, v92
	ds_bpermute_b32 v95, v86, v94
	ds_bpermute_b32 v97, v86, v96
	ds_bpermute_b32 v71, v86, v70
	s_waitcnt lgkmcnt(3)
	v_add_f32_e32 v92, v92, v93
	s_waitcnt lgkmcnt(2)
	v_add_f32_e32 v94, v94, v95
	s_waitcnt lgkmcnt(1)
	v_add_f32_e32 v96, v96, v97
	s_waitcnt lgkmcnt(0)
	v_add_f32_e32 v70, v70, v71
	ds_bpermute_b32 v93, v87, v92
	ds_bpermute_b32 v95, v87, v94
	ds_bpermute_b32 v97, v87, v96
	ds_bpermute_b32 v71, v87, v70
	s_waitcnt lgkmcnt(3)
	v_add_f32_e32 v92, v92, v93
	s_waitcnt lgkmcnt(2)
	v_add_f32_e32 v94, v94, v95
	s_waitcnt lgkmcnt(1)
	v_add_f32_e32 v96, v96, v97
	s_waitcnt lgkmcnt(0)
	v_add_f32_e32 v70, v70, v71
	ds_bpermute_b32 v93, v88, v92
	ds_bpermute_b32 v95, v88, v94
	ds_bpermute_b32 v97, v88, v96
	ds_bpermute_b32 v71, v88, v70
	s_waitcnt lgkmcnt(3)
	v_add_f32_e32 v92, v92, v93
	s_waitcnt lgkmcnt(2)
	v_add_f32_e32 v94, v94, v95
	s_waitcnt lgkmcnt(1)
	v_add_f32_e32 v96, v96, v97
	s_waitcnt lgkmcnt(0)
	v_add_f32_e32 v70, v70, v71
	ds_bpermute_b32 v93, v89, v92
	ds_bpermute_b32 v95, v89, v94
	ds_bpermute_b32 v97, v89, v96
	ds_bpermute_b32 v71, v89, v70
	s_waitcnt lgkmcnt(3)
	v_add_f32_e32 v92, v92, v93
	s_waitcnt lgkmcnt(2)
	v_add_f32_e32 v94, v94, v95
	s_waitcnt lgkmcnt(1)
	v_add_f32_e32 v96, v96, v97
	s_waitcnt lgkmcnt(0)
	v_add_f32_e32 v70, v70, v71
	ds_bpermute_b32 v93, v90, v92
	ds_bpermute_b32 v95, v90, v94
	ds_bpermute_b32 v97, v90, v96
	ds_bpermute_b32 v71, v90, v70
	s_waitcnt lgkmcnt(3)
	v_add_f32_e32 v92, v92, v93
	s_waitcnt lgkmcnt(2)
	v_add_f32_e32 v94, v94, v95
	s_waitcnt lgkmcnt(1)
	v_add_f32_e32 v96, v96, v97
	s_waitcnt lgkmcnt(0)
	v_add_f32_e32 v70, v70, v71
	ds_bpermute_b32 v93, v91, v92
	ds_bpermute_b32 v95, v91, v94
	ds_bpermute_b32 v97, v91, v96
	ds_bpermute_b32 v72, v91, v70
	s_and_saveexec_b64 s[14:15], vcc
	s_cbranch_execz .LBB0_412
	s_waitcnt lgkmcnt(3)
	v_add_f32_e32 v71, v92, v93
	v_cmp_lt_i32_e64 s[0:1], 0, v200
	s_and_saveexec_b64 s[16:17], s[0:1]
	s_cbranch_execz .LBB0_411
	v_cmp_ne_u32_e64 s[0:1], 1, v200
	s_and_saveexec_b64 s[26:27], s[0:1]
	s_xor_b64 s[0:1], exec, s[26:27]
	s_cbranch_execz .LBB0_417
	s_waitcnt lgkmcnt(1)
	v_add_f32_e32 v71, v96, v97
	s_waitcnt lgkmcnt(0)
	v_add_f32_e32 v70, v70, v72
	v_cndmask_b32_e64 v71, v70, v71, s[4:5]

.LBB0_420:
	v_lshlrev_b32_e32 v190, 2, v1
	v_lshl_add_u64 v[50:51], s[6:7], 0, v[190:191]
	s_mov_b64 s[0:1], 0x8000
	v_lshl_add_u64 v[14:15], v[50:51], 0, s[0:1]
	v_add_co_u32_e32 v2, vcc, 0x8000, v50
	s_mov_b64 s[0:1], 0x9000
	s_nop 0
	v_addc_co_u32_e32 v3, vcc, 0, v51, vcc
	s_waitcnt vmcnt(2)
	v_lshl_add_u64 v[18:19], v[50:51], 0, s[0:1]
	s_mov_b32 s0, 0x9000
	v_add_co_u32_e32 v22, vcc, s0, v50
	s_mov_b32 s0, 0xa000
	s_nop 0
	v_addc_co_u32_e32 v23, vcc, 0, v51, vcc
	v_add_co_u32_e32 v58, vcc, s0, v50
	s_mov_b64 s[0:1], 0x9800
	v_lshl_add_u64 v[26:27], v[50:51], 0, s[0:1]
	s_mov_b64 s[0:1], 0xa000
	v_lshl_add_u64 v[30:31], v[50:51], 0, s[0:1]
	s_mov_b64 s[0:1], 0xa800
	v_lshl_add_u64 v[42:43], v[50:51], 0, s[0:1]
	s_mov_b64 s[0:1], 0xb000
	v_addc_co_u32_e32 v59, vcc, 0, v51, vcc
	v_lshl_add_u64 v[46:47], v[50:51], 0, s[0:1]
	s_mov_b32 s0, 0xb000
	v_add_co_u32_e32 v54, vcc, s0, v50
	s_mov_b64 s[0:1], 0xb800
	s_nop 0
	v_addc_co_u32_e32 v55, vcc, 0, v51, vcc
	v_lshl_add_u64 v[62:63], v[50:51], 0, s[0:1]
	global_load_dwordx4 v[2:5], v[2:3], off
	s_waitcnt lgkmcnt(1)
	global_load_dwordx4 v[6:9], v[14:15], off offset:2064
	s_waitcnt lgkmcnt(0)
	global_load_dwordx4 v[10:13], v[14:15], off offset:16
	s_nop 0
	global_load_dwordx4 v[14:17], v[14:15], off offset:2048
	s_nop 0
	global_load_dwordx4 v[18:21], v[18:19], off offset:16
	s_nop 0
	global_load_dwordx4 v[22:25], v[22:23], off offset:2048
	s_nop 0
	global_load_dwordx4 v[26:29], v[26:27], off offset:16
	s_nop 0
	global_load_dwordx4 v[30:33], v[30:31], off offset:16
	s_nop 0
	global_load_dwordx4 v[34:37], v[58:59], off
	global_load_dwordx4 v[38:41], v[58:59], off offset:2048
	s_nop 0
	global_load_dwordx4 v[42:45], v[42:43], off offset:16
	s_nop 0
	global_load_dwordx4 v[46:49], v[46:47], off offset:16
	s_nop 0
	global_load_dwordx4 v[50:53], v[54:55], off
	s_nop 0
	global_load_dwordx4 v[54:57], v[54:55], off offset:2048
	s_nop 0
	global_load_dwordx4 v[58:61], v[58:59], off offset:-4096
	s_nop 0
	global_load_dwordx4 v[62:65], v[62:63], off offset:16
	v_and_b32_e32 v66, 64, v227
	v_add_u32_e32 v66, 64, v66
	v_xor_b32_e32 v67, 1, v227
	v_cmp_lt_i32_e32 vcc, v67, v66
	s_ashr_i32 s91, s90, 31
	s_lshl_b32 s6, s2, 2
	v_cndmask_b32_e32 v67, v227, v67, vcc
	v_lshlrev_b32_e32 v86, 2, v67
	v_xor_b32_e32 v67, 2, v227
	v_cmp_lt_i32_e32 vcc, v67, v66
	s_lshl_b64 s[0:1], s[90:91], 2
	s_add_u32 s0, s6, s0
	v_cndmask_b32_e32 v67, v227, v67, vcc
	v_lshlrev_b32_e32 v87, 2, v67
	v_xor_b32_e32 v67, 4, v227
	v_cmp_lt_i32_e32 vcc, v67, v66
	s_addc_u32 s1, 0, s1
	s_add_u32 s0, s34, s0
	v_cndmask_b32_e32 v67, v227, v67, vcc
	v_lshlrev_b32_e32 v88, 2, v67
	v_xor_b32_e32 v67, 8, v227
	v_cmp_lt_i32_e32 vcc, v67, v66
	s_addc_u32 s1, s35, s1
	s_ashr_i32 s93, s92, 31
	v_cndmask_b32_e32 v67, v227, v67, vcc
	v_lshlrev_b32_e32 v89, 2, v67
	v_xor_b32_e32 v67, 16, v227
	v_cmp_lt_i32_e32 vcc, v67, v66
	s_lshl_b64 s[6:7], s[92:93], 2
	v_readlane_b32 s8, v255, 54
	v_cndmask_b32_e32 v67, v227, v67, vcc
	v_lshlrev_b32_e32 v90, 2, v67
	v_xor_b32_e32 v67, 32, v227
	v_cmp_lt_i32_e32 vcc, v67, v66
	v_readlane_b32 s9, v255, 55
	v_cmp_eq_u32_e64 s[4:5], 2, v200
	v_cndmask_b32_e32 v66, v227, v67, vcc
	v_lshlrev_b32_e32 v91, 2, v66
	v_mul_u32_u24_e32 v66, 0x1600, v200
	v_lshlrev_b32_e32 v190, 2, v66
	v_lshl_add_u64 v[66:67], s[0:1], 0, v[190:191]
	s_mov_b64 s[0:1], 0xa22000
	v_lshl_add_u64 v[66:67], v[66:67], 0, s[0:1]
	s_lshl_b64 s[0:1], s[90:91], 11
	s_add_u32 s0, s8, s0
	v_lshlrev_b32_e32 v190, 4, v200
	s_addc_u32 s1, s9, s1
	v_lshl_add_u64 v[68:69], s[0:1], 0, v[190:191]
	s_mov_b64 s[0:1], 0x1c00000
	v_cmp_gt_u32_e32 vcc, 4, v200
	v_lshl_add_u64 v[68:69], v[68:69], 0, s[0:1]
	s_lshl_b64 s[8:9], s[92:93], 11
	s_mov_b32 s14, s90
	global_load_dwordx4 v[104:107], v[68:69], off
	global_load_dwordx4 v[108:111], v[68:69], off offset:1024
	s_branch .LBB0_424

.LBB0_424:
	s_waitcnt lgkmcnt(0)
	s_waitcnt vmcnt(0)
	v_mov_b32_e32 v70, v104
	v_mov_b32_e32 v71, v105
	v_mov_b32_e32 v72, v106
	v_mov_b32_e32 v73, v107
	v_mov_b32_e32 v92, v108
	v_mov_b32_e32 v93, v109
	v_mov_b32_e32 v94, v110
	v_mov_b32_e32 v95, v111
	v_lshl_add_u64 v[112:113], v[68:69], 0, s[8:9]
	global_load_dwordx4 v[104:107], v[112:113], off
	global_load_dwordx4 v[108:111], v[112:113], off offset:1024
	v_lshlrev_b32_e32 v84, 16, v72
	v_and_b32_e32 v85, 0xffff0000, v72
	v_lshlrev_b32_e32 v82, 16, v73
	v_and_b32_e32 v83, 0xffff0000, v73
	v_lshlrev_b32_e32 v78, 16, v70
	v_and_b32_e32 v79, 0xffff0000, v70
	v_lshlrev_b32_e32 v80, 16, v71
	v_and_b32_e32 v81, 0xffff0000, v71
	v_lshlrev_b32_e32 v76, 16, v92
	v_and_b32_e32 v77, 0xffff0000, v92
	v_lshlrev_b32_e32 v74, 16, v93
	v_and_b32_e32 v75, 0xffff0000, v93
	v_lshlrev_b32_e32 v70, 16, v94
	v_and_b32_e32 v71, 0xffff0000, v94
	v_lshlrev_b32_e32 v72, 16, v95
	v_and_b32_e32 v73, 0xffff0000, v95
	v_pk_mul_f32 v[92:93], v[10:11], v[84:85]
	v_pk_mul_f32 v[94:95], v[12:13], v[82:83]
	v_pk_fma_f32 v[92:93], v[2:3], v[78:79], v[92:93]
	v_pk_fma_f32 v[94:95], v[4:5], v[80:81], v[94:95]
	v_pk_fma_f32 v[92:93], v[14:15], v[76:77], v[92:93]
	v_pk_fma_f32 v[94:95], v[16:17], v[74:75], v[94:95]
	v_pk_fma_f32 v[92:93], v[6:7], v[70:71], v[92:93]
	v_pk_fma_f32 v[94:95], v[8:9], v[72:73], v[94:95]
	v_add_f32_e32 v92, v92, v93
	v_add_f32_e32 v93, v94, v95
	v_pk_mul_f32 v[94:95], v[18:19], v[84:85]
	v_pk_mul_f32 v[96:97], v[20:21], v[82:83]
	v_pk_fma_f32 v[94:95], v[58:59], v[78:79], v[94:95]
	v_pk_fma_f32 v[96:97], v[60:61], v[80:81], v[96:97]
	v_pk_fma_f32 v[94:95], v[22:23], v[76:77], v[94:95]
	v_pk_fma_f32 v[96:97], v[24:25], v[74:75], v[96:97]
	v_pk_fma_f32 v[94:95], v[26:27], v[70:71], v[94:95]
	v_pk_fma_f32 v[96:97], v[28:29], v[72:73], v[96:97]
	v_add_f32_e32 v94, v94, v95
	v_add_f32_e32 v95, v96, v97
	v_pk_mul_f32 v[96:97], v[30:31], v[84:85]
	v_pk_mul_f32 v[98:99], v[32:33], v[82:83]
	v_pk_mul_f32 v[84:85], v[46:47], v[84:85]
	v_pk_mul_f32 v[82:83], v[48:49], v[82:83]
	v_pk_fma_f32 v[98:99], v[36:37], v[80:81], v[98:99]
	v_pk_fma_f32 v[96:97], v[34:35], v[78:79], v[96:97]
	v_pk_fma_f32 v[80:81], v[52:53], v[80:81], v[82:83]
	v_pk_fma_f32 v[78:79], v[50:51], v[78:79], v[84:85]
	v_pk_fma_f32 v[96:97], v[38:39], v[76:77], v[96:97]
	v_pk_fma_f32 v[98:99], v[40:41], v[74:75], v[98:99]
	v_pk_fma_f32 v[76:77], v[54:55], v[76:77], v[78:79]
	v_pk_fma_f32 v[74:75], v[56:57], v[74:75], v[80:81]
	v_pk_fma_f32 v[98:99], v[44:45], v[72:73], v[98:99]
	v_pk_fma_f32 v[96:97], v[42:43], v[70:71], v[96:97]
	v_pk_fma_f32 v[72:73], v[64:65], v[72:73], v[74:75]
	v_pk_fma_f32 v[70:71], v[62:63], v[70:71], v[76:77]
	v_add_f32_e32 v96, v96, v97
	v_add_f32_e32 v97, v98, v99
	v_add_f32_e32 v70, v70, v71
	v_add_f32_e32 v71, v72, v73
	v_add_f32_e32 v92, v92, v93
	v_add_f32_e32 v94, v94, v95
	v_add_f32_e32 v96, v96, v97
	v_add_f32_e32 v70, v70, v71
	ds_bpermute_b32 v93, v86, v92
	ds_bpermute_b32 v95, v86, v94
	ds_bpermute_b32 v97, v86, v96
	ds_bpermute_b32 v71, v86, v70
	s_waitcnt lgkmcnt(3)
	v_add_f32_e32 v92, v92, v93
	s_waitcnt lgkmcnt(2)
	v_add_f32_e32 v94, v94, v95
	s_waitcnt lgkmcnt(1)
	v_add_f32_e32 v96, v96, v97
	s_waitcnt lgkmcnt(0)
	v_add_f32_e32 v70, v70, v71
	ds_bpermute_b32 v93, v87, v92
	ds_bpermute_b32 v95, v87, v94
	ds_bpermute_b32 v97, v87, v96
	ds_bpermute_b32 v71, v87, v70
	s_waitcnt lgkmcnt(3)
	v_add_f32_e32 v92, v92, v93
	s_waitcnt lgkmcnt(2)
	v_add_f32_e32 v94, v94, v95
	s_waitcnt lgkmcnt(1)
	v_add_f32_e32 v96, v96, v97
	s_waitcnt lgkmcnt(0)
	v_add_f32_e32 v70, v70, v71
	ds_bpermute_b32 v93, v88, v92
	ds_bpermute_b32 v95, v88, v94
	ds_bpermute_b32 v97, v88, v96
	ds_bpermute_b32 v71, v88, v70
	s_waitcnt lgkmcnt(3)
	v_add_f32_e32 v92, v92, v93
	s_waitcnt lgkmcnt(2)
	v_add_f32_e32 v94, v94, v95
	s_waitcnt lgkmcnt(1)
	v_add_f32_e32 v96, v96, v97
	s_waitcnt lgkmcnt(0)
	v_add_f32_e32 v70, v70, v71
	ds_bpermute_b32 v93, v89, v92
	ds_bpermute_b32 v95, v89, v94
	ds_bpermute_b32 v97, v89, v96
	ds_bpermute_b32 v71, v89, v70
	s_waitcnt lgkmcnt(3)
	v_add_f32_e32 v92, v92, v93
	s_waitcnt lgkmcnt(2)
	v_add_f32_e32 v94, v94, v95
	s_waitcnt lgkmcnt(1)
	v_add_f32_e32 v96, v96, v97
	s_waitcnt lgkmcnt(0)
	v_add_f32_e32 v70, v70, v71
	ds_bpermute_b32 v93, v90, v92
	ds_bpermute_b32 v95, v90, v94
	ds_bpermute_b32 v97, v90, v96
	ds_bpermute_b32 v71, v90, v70
	s_waitcnt lgkmcnt(3)
	v_add_f32_e32 v92, v92, v93
	s_waitcnt lgkmcnt(2)
	v_add_f32_e32 v94, v94, v95
	s_waitcnt lgkmcnt(1)
	v_add_f32_e32 v96, v96, v97
	s_waitcnt lgkmcnt(0)
	v_add_f32_e32 v70, v70, v71
	ds_bpermute_b32 v93, v91, v92
	ds_bpermute_b32 v95, v91, v94
	ds_bpermute_b32 v97, v91, v96
	ds_bpermute_b32 v72, v91, v70
	s_and_saveexec_b64 s[10:11], vcc
	s_cbranch_execz .LBB0_423
	s_waitcnt lgkmcnt(3)
	v_add_f32_e32 v71, v92, v93
	v_cmp_lt_i32_e64 s[0:1], 0, v200
	s_and_saveexec_b64 s[12:13], s[0:1]
	s_cbranch_execz .LBB0_422
	v_cmp_ne_u32_e64 s[0:1], 1, v200
	s_and_saveexec_b64 s[16:17], s[0:1]
	s_xor_b64 s[0:1], exec, s[16:17]
	s_cbranch_execz .LBB0_428
	s_waitcnt lgkmcnt(1)
	v_add_f32_e32 v71, v96, v97
	s_waitcnt lgkmcnt(0)
	v_add_f32_e32 v70, v70, v72
	v_cndmask_b32_e64 v71, v70, v71, s[4:5]

.LBB0_433:
	s_cmpk_gt_i32 s90, 0xbff
	s_cbranch_scc1 .LBB0_446
	v_lshlrev_b32_e32 v190, 2, v1
	v_lshl_add_u64 v[58:59], s[34:35], 0, v[190:191]
	s_mov_b64 s[0:1], 0x964000
	v_add_co_u32_e32 v2, vcc, 0x964000, v58
	v_lshl_add_u64 v[14:15], v[58:59], 0, s[0:1]
	s_nop 0
	v_addc_co_u32_e32 v3, vcc, 0, v59, vcc
	s_mov_b64 s[0:1], 0x965000
	s_waitcnt vmcnt(3)
	v_lshl_add_u64 v[22:23], v[58:59], 0, s[0:1]
	v_add_co_u32_e32 v26, vcc, 0x965000, v58
	s_mov_b64 s[0:1], 0x965800
	s_nop 0
	v_addc_co_u32_e32 v27, vcc, 0, v59, vcc
	v_lshl_add_u64 v[30:31], v[58:59], 0, s[0:1]
	s_mov_b64 s[0:1], 0x966000
	v_lshl_add_u64 v[38:39], v[58:59], 0, s[0:1]
	v_add_co_u32_e32 v42, vcc, 0x966000, v58
	s_mov_b64 s[0:1], 0x966800
	s_nop 0
	v_addc_co_u32_e32 v43, vcc, 0, v59, vcc
	v_lshl_add_u64 v[46:47], v[58:59], 0, s[0:1]
	s_mov_b64 s[0:1], 0x967000
	global_load_dwordx4 v[2:5], v[2:3], off
	s_waitcnt lgkmcnt(1)
	global_load_dwordx4 v[6:9], v[14:15], off offset:2064
	s_waitcnt lgkmcnt(0)
	global_load_dwordx4 v[10:13], v[14:15], off offset:16
	s_nop 0
	global_load_dwordx4 v[14:17], v[14:15], off offset:2048
	v_lshl_add_u64 v[54:55], v[58:59], 0, s[0:1]
	v_add_co_u32_e32 v60, vcc, 0x967000, v58
	s_mov_b64 s[0:1], 0x967800
	s_nop 0
	v_addc_co_u32_e32 v61, vcc, 0, v59, vcc
	v_lshl_add_u64 v[62:63], v[58:59], 0, s[0:1]
	global_load_dwordx4 v[18:21], v[26:27], off
	s_nop 0
	global_load_dwordx4 v[22:25], v[22:23], off offset:16
	s_nop 0
	global_load_dwordx4 v[26:29], v[26:27], off offset:2048
	s_nop 0
	global_load_dwordx4 v[30:33], v[30:31], off offset:16
	s_nop 0
	global_load_dwordx4 v[34:37], v[42:43], off
	s_nop 0
	global_load_dwordx4 v[38:41], v[38:39], off offset:16
	s_nop 0
	global_load_dwordx4 v[42:45], v[42:43], off offset:2048
	s_nop 0
	global_load_dwordx4 v[46:49], v[46:47], off offset:16
	s_nop 0
	global_load_dwordx4 v[50:53], v[60:61], off
	s_nop 0
	global_load_dwordx4 v[54:57], v[54:55], off offset:16
	s_nop 0
	global_load_dwordx4 v[58:61], v[60:61], off offset:2048
	s_nop 0
	global_load_dwordx4 v[62:65], v[62:63], off offset:16
	v_and_b32_e32 v1, 64, v227
	v_add_u32_e32 v66, 64, v1
	v_xor_b32_e32 v1, 1, v227
	v_cmp_lt_i32_e32 vcc, v1, v66
	v_xor_b32_e32 v67, 2, v227
	s_ashr_i32 s91, s90, 31
	v_cndmask_b32_e32 v1, v227, v1, vcc
	v_cmp_lt_i32_e32 vcc, v67, v66
	s_lshl_b32 s2, s2, 2
	s_lshl_b64 s[0:1], s[90:91], 2
	v_cndmask_b32_e32 v67, v227, v67, vcc
	v_lshlrev_b32_e32 v86, 2, v67
	v_xor_b32_e32 v67, 4, v227
	v_cmp_lt_i32_e32 vcc, v67, v66
	s_add_u32 s0, s2, s0
	s_addc_u32 s1, 0, s1
	v_cndmask_b32_e32 v67, v227, v67, vcc
	v_lshlrev_b32_e32 v87, 2, v67
	v_xor_b32_e32 v67, 8, v227
	v_cmp_lt_i32_e32 vcc, v67, v66
	s_add_u32 s0, s34, s0
	s_addc_u32 s1, s35, s1
	v_cndmask_b32_e32 v67, v227, v67, vcc
	v_lshlrev_b32_e32 v88, 2, v67
	v_xor_b32_e32 v67, 16, v227
	v_cmp_lt_i32_e32 vcc, v67, v66
	s_ashr_i32 s93, s92, 31
	s_lshl_b64 s[6:7], s[92:93], 2
	v_cndmask_b32_e32 v67, v227, v67, vcc
	v_lshlrev_b32_e32 v89, 2, v67
	v_xor_b32_e32 v67, 32, v227
	v_cmp_lt_i32_e32 vcc, v67, v66
	v_readlane_b32 s2, v255, 54
	v_readlane_b32 s3, v255, 55
	v_cndmask_b32_e32 v66, v227, v67, vcc
	v_lshlrev_b32_e32 v90, 2, v66
	v_mul_u32_u24_e32 v66, 0xc00, v200
	v_lshlrev_b32_e32 v190, 2, v66
	v_lshl_add_u64 v[66:67], s[0:1], 0, v[190:191]
	s_mov_b64 s[0:1], 0xa38000
	v_lshl_add_u64 v[66:67], v[66:67], 0, s[0:1]
	s_lshl_b64 s[0:1], s[90:91], 11
	s_add_u32 s0, s2, s0
	v_lshlrev_b32_e32 v190, 4, v200
	s_addc_u32 s1, s3, s1
	v_lshl_add_u64 v[68:69], s[0:1], 0, v[190:191]
	s_mov_b64 s[0:1], 0x3500000
	v_lshlrev_b32_e32 v1, 2, v1
	v_cmp_gt_u32_e32 vcc, 4, v200
	v_cmp_eq_u32_e64 s[4:5], 2, v200
	v_lshl_add_u64 v[68:69], v[68:69], 0, s[0:1]
	s_lshl_b64 s[8:9], s[92:93], 11
	s_mov_b32 s2, s90
	global_load_dwordx4 v[104:107], v[68:69], off
	global_load_dwordx4 v[108:111], v[68:69], off offset:1024
	s_branch .LBB0_438

.LBB0_438:
	s_waitcnt lgkmcnt(0)
	s_waitcnt vmcnt(0)
	v_mov_b32_e32 v70, v104
	v_mov_b32_e32 v71, v105
	v_mov_b32_e32 v72, v106
	v_mov_b32_e32 v73, v107
	v_mov_b32_e32 v92, v108
	v_mov_b32_e32 v93, v109
	v_mov_b32_e32 v94, v110
	v_mov_b32_e32 v95, v111
	v_lshl_add_u64 v[112:113], v[68:69], 0, s[8:9]
	global_load_dwordx4 v[104:107], v[112:113], off
	global_load_dwordx4 v[108:111], v[112:113], off offset:1024
	v_lshlrev_b32_e32 v84, 16, v72
	v_and_b32_e32 v85, 0xffff0000, v72
	v_lshlrev_b32_e32 v82, 16, v73
	v_and_b32_e32 v83, 0xffff0000, v73
	v_lshlrev_b32_e32 v78, 16, v70
	v_and_b32_e32 v79, 0xffff0000, v70
	v_lshlrev_b32_e32 v80, 16, v71
	v_and_b32_e32 v81, 0xffff0000, v71
	v_lshlrev_b32_e32 v76, 16, v92
	v_and_b32_e32 v77, 0xffff0000, v92
	v_lshlrev_b32_e32 v74, 16, v93
	v_and_b32_e32 v75, 0xffff0000, v93
	v_lshlrev_b32_e32 v70, 16, v94
	v_and_b32_e32 v71, 0xffff0000, v94
	v_lshlrev_b32_e32 v72, 16, v95
	v_and_b32_e32 v73, 0xffff0000, v95
	v_pk_mul_f32 v[92:93], v[10:11], v[84:85]
	v_pk_mul_f32 v[94:95], v[12:13], v[82:83]
	v_pk_fma_f32 v[92:93], v[2:3], v[78:79], v[92:93]
	v_pk_fma_f32 v[94:95], v[4:5], v[80:81], v[94:95]
	v_pk_fma_f32 v[92:93], v[14:15], v[76:77], v[92:93]
	v_pk_fma_f32 v[94:95], v[16:17], v[74:75], v[94:95]
	v_pk_fma_f32 v[92:93], v[6:7], v[70:71], v[92:93]
	v_pk_fma_f32 v[94:95], v[8:9], v[72:73], v[94:95]
	v_add_f32_e32 v91, v92, v93
	v_add_f32_e32 v92, v94, v95
	v_pk_mul_f32 v[94:95], v[22:23], v[84:85]
	v_pk_mul_f32 v[96:97], v[24:25], v[82:83]
	v_pk_fma_f32 v[94:95], v[18:19], v[78:79], v[94:95]
	v_pk_fma_f32 v[96:97], v[20:21], v[80:81], v[96:97]
	v_pk_fma_f32 v[94:95], v[26:27], v[76:77], v[94:95]
	v_pk_fma_f32 v[96:97], v[28:29], v[74:75], v[96:97]
	v_pk_fma_f32 v[94:95], v[30:31], v[70:71], v[94:95]
	v_pk_fma_f32 v[96:97], v[32:33], v[72:73], v[96:97]
	v_add_f32_e32 v93, v94, v95
	v_add_f32_e32 v94, v96, v97
	v_pk_mul_f32 v[96:97], v[38:39], v[84:85]
	v_pk_mul_f32 v[98:99], v[40:41], v[82:83]
	v_pk_mul_f32 v[84:85], v[54:55], v[84:85]
	v_pk_mul_f32 v[82:83], v[56:57], v[82:83]
	v_pk_fma_f32 v[98:99], v[36:37], v[80:81], v[98:99]
	v_pk_fma_f32 v[96:97], v[34:35], v[78:79], v[96:97]
	v_pk_fma_f32 v[80:81], v[52:53], v[80:81], v[82:83]
	v_pk_fma_f32 v[78:79], v[50:51], v[78:79], v[84:85]
	v_pk_fma_f32 v[96:97], v[42:43], v[76:77], v[96:97]
	v_pk_fma_f32 v[98:99], v[44:45], v[74:75], v[98:99]
	v_pk_fma_f32 v[76:77], v[58:59], v[76:77], v[78:79]
	v_pk_fma_f32 v[74:75], v[60:61], v[74:75], v[80:81]
	v_pk_fma_f32 v[98:99], v[48:49], v[72:73], v[98:99]
	v_pk_fma_f32 v[96:97], v[46:47], v[70:71], v[96:97]
	v_pk_fma_f32 v[72:73], v[64:65], v[72:73], v[74:75]
	v_pk_fma_f32 v[70:71], v[62:63], v[70:71], v[76:77]
	v_add_f32_e32 v95, v96, v97
	v_add_f32_e32 v96, v98, v99
	v_add_f32_e32 v70, v70, v71
	v_add_f32_e32 v71, v72, v73
	v_add_f32_e32 v91, v91, v92
	v_add_f32_e32 v93, v93, v94
	v_add_f32_e32 v95, v95, v96
	v_add_f32_e32 v70, v70, v71
	ds_bpermute_b32 v92, v1, v91
	ds_bpermute_b32 v94, v1, v93
	ds_bpermute_b32 v96, v1, v95
	ds_bpermute_b32 v71, v1, v70
	s_waitcnt lgkmcnt(3)
	v_add_f32_e32 v91, v91, v92
	s_waitcnt lgkmcnt(2)
	v_add_f32_e32 v93, v93, v94
	s_waitcnt lgkmcnt(1)
	v_add_f32_e32 v95, v95, v96
	s_waitcnt lgkmcnt(0)
	v_add_f32_e32 v70, v70, v71
	ds_bpermute_b32 v92, v86, v91
	ds_bpermute_b32 v94, v86, v93
	ds_bpermute_b32 v96, v86, v95
	ds_bpermute_b32 v71, v86, v70
	s_waitcnt lgkmcnt(3)
	v_add_f32_e32 v91, v91, v92
	s_waitcnt lgkmcnt(2)
	v_add_f32_e32 v93, v93, v94
	s_waitcnt lgkmcnt(1)
	v_add_f32_e32 v95, v95, v96
	s_waitcnt lgkmcnt(0)
	v_add_f32_e32 v70, v70, v71
	ds_bpermute_b32 v92, v87, v91
	ds_bpermute_b32 v94, v87, v93
	ds_bpermute_b32 v96, v87, v95
	ds_bpermute_b32 v71, v87, v70
	s_waitcnt lgkmcnt(3)
	v_add_f32_e32 v91, v91, v92
	s_waitcnt lgkmcnt(2)
	v_add_f32_e32 v93, v93, v94
	s_waitcnt lgkmcnt(1)
	v_add_f32_e32 v95, v95, v96
	s_waitcnt lgkmcnt(0)
	v_add_f32_e32 v70, v70, v71
	ds_bpermute_b32 v92, v88, v91
	ds_bpermute_b32 v94, v88, v93
	ds_bpermute_b32 v96, v88, v95
	ds_bpermute_b32 v71, v88, v70
	s_waitcnt lgkmcnt(3)
	v_add_f32_e32 v91, v91, v92
	s_waitcnt lgkmcnt(2)
	v_add_f32_e32 v93, v93, v94
	s_waitcnt lgkmcnt(1)
	v_add_f32_e32 v95, v95, v96
	s_waitcnt lgkmcnt(0)
	v_add_f32_e32 v70, v70, v71
	ds_bpermute_b32 v92, v89, v91
	ds_bpermute_b32 v94, v89, v93
	ds_bpermute_b32 v96, v89, v95
	ds_bpermute_b32 v71, v89, v70
	s_waitcnt lgkmcnt(3)
	v_add_f32_e32 v91, v91, v92
	s_waitcnt lgkmcnt(2)
	v_add_f32_e32 v93, v93, v94
	s_waitcnt lgkmcnt(1)
	v_add_f32_e32 v95, v95, v96
	s_waitcnt lgkmcnt(0)
	v_add_f32_e32 v70, v70, v71
	ds_bpermute_b32 v92, v90, v91
	ds_bpermute_b32 v94, v90, v93
	ds_bpermute_b32 v96, v90, v95
	ds_bpermute_b32 v72, v90, v70
	s_and_saveexec_b64 s[10:11], vcc
	s_cbranch_execz .LBB0_437
	s_waitcnt lgkmcnt(3)
	v_add_f32_e32 v71, v91, v92
	v_cmp_lt_i32_e64 s[0:1], 0, v200
	s_and_saveexec_b64 s[12:13], s[0:1]
	s_cbranch_execz .LBB0_436
	v_cmp_ne_u32_e64 s[0:1], 1, v200
	s_and_saveexec_b64 s[14:15], s[0:1]
	s_xor_b64 s[0:1], exec, s[14:15]
	s_cbranch_execz .LBB0_442
	s_waitcnt lgkmcnt(1)
	v_add_f32_e32 v71, v95, v96
	s_waitcnt lgkmcnt(0)
	v_add_f32_e32 v70, v70, v72
	v_cndmask_b32_e64 v71, v70, v71, s[4:5]
